# v202 + tile-scheduler r/gsz division replaced by shifts in P2/P4/P9 unit loops (unpadded)
# speedup vs baseline: 1.0056x; 1.0019x over previous
.LBB0_122:
	s_add_i32 s86, s86, 1
	s_mul_i32 s2, s86, s89
	s_mul_hi_u32 s3, s86, s33
	s_add_i32 s3, s3, s2
	s_mul_i32 s2, s86, s33
	s_add_u32 s30, s2, s10
	s_addc_u32 s31, s3, s81
	v_cmp_gt_i64_e32 vcc, s[30:31], v[132:133]
	v_cmp_lt_i64_e64 s[2:3], s[30:31], v[130:131]
	s_cbranch_vccnz .LBB0_124
	s_ashr_i32 s8, s30, 31
	s_lshr_b32 s8, s8, 29
	s_add_i32 s8, s30, s8
	s_ashr_i32 s9, s8, 3
	s_and_b32 s8, s8, -8
	s_sub_i32 s8, s30, s8
	s_cmp_lt_i32 s8, 0
	s_cselect_b32 s11, s82, 0xb0
	s_mul_i32 s8, s8, s11
	s_add_i32 s8, s8, s9
	s_mul_hi_i32 s9, s8, 0x2e8ba2e9
	s_lshr_b32 s11, s9, 31
	s_ashr_i32 s9, s9, 4
	s_add_i32 s9, s9, s11
	s_lshl_b32 s11, s9, 2
	s_mulk_i32 s9, 0x58
	s_sub_i32 s8, s8, s9
	s_lshr_b32 s20, s8, 2
	s_and_b32 s8, s8, 3
	s_add_i32 s28, s11, s8

.LBB0_325:
	s_add_i32 s88, s88, 1
	s_mul_i32 s2, s88, s91
	s_mul_hi_u32 s3, s88, s33
	s_add_i32 s3, s3, s2
	s_mul_i32 s2, s88, s33
	s_add_u32 s64, s2, s10
	s_addc_u32 s65, s3, s82
	v_cmp_gt_i64_e32 vcc, s[64:65], v[132:133]
	v_cmp_lt_i64_e64 s[2:3], s[64:65], v[130:131]
	s_cbranch_vccnz .LBB0_327
	s_ashr_i32 s8, s64, 31
	s_lshr_b32 s8, s8, 29
	s_add_i32 s8, s64, s8
	s_ashr_i32 s9, s8, 3
	s_and_b32 s8, s8, -8
	s_sub_i32 s8, s64, s8
	s_cmp_lt_i32 s8, 0
	s_cselect_b32 s11, s83, 0x60
	s_mul_i32 s8, s8, s11
	s_add_i32 s8, s8, s9
	s_mul_hi_i32 s9, s8, 0x2aaaaaab
	s_lshr_b32 s11, s9, 31
	s_ashr_i32 s9, s9, 3
	s_add_i32 s9, s9, s11
	s_lshl_b32 s11, s9, 2
	s_mul_i32 s9, s9, 48
	s_sub_i32 s8, s8, s9
	s_lshr_b32 s20, s8, 2
	s_and_b32 s8, s8, 3
	s_add_i32 s26, s11, s8

.LBB0_616:
	s_add_i32 s68, s68, 1
	s_mul_i32 s2, s68, s71
	s_mul_hi_u32 s3, s68, s33
	s_add_i32 s3, s3, s2
	s_mul_i32 s2, s68, s33
	s_add_u32 s26, s2, s10
	s_addc_u32 s27, s3, s63
	v_cmp_gt_i64_e32 vcc, s[26:27], v[132:133]
	v_cmp_lt_i64_e64 s[2:3], s[26:27], v[130:131]
	s_cbranch_vccnz .LBB0_618
	s_ashr_i32 s8, s26, 31
	s_lshr_b32 s8, s8, 29
	s_add_i32 s8, s26, s8
	s_ashr_i32 s9, s8, 3
	s_and_b32 s8, s8, -8
	s_sub_i32 s8, s26, s8
	s_cmp_lt_i32 s8, 0
	s_cselect_b32 s11, s64, 0xb0
	s_mul_i32 s8, s8, s11
	s_add_i32 s8, s8, s9
	s_mul_hi_i32 s9, s8, 0x2e8ba2e9
	s_lshr_b32 s11, s9, 31
	s_ashr_i32 s9, s9, 4
	s_add_i32 s9, s9, s11
	s_lshl_b32 s11, s9, 2
	s_mulk_i32 s9, 0x58
	s_sub_i32 s8, s8, s9
	s_lshr_b32 s18, s8, 2
	s_and_b32 s8, s8, 3
	s_add_i32 s20, s11, s8
